# counted waits in the branch GEMM gate passes: each row-block waits only for its own gate words (vmcnt(15-k) in ratio passes, vmcnt(15) in storing passes) instead of vmcnt(0) behind all loads; on top o
# speedup vs baseline: 1.0027x; 1.0027x over previous
.LBB0_750:
	s_cmp_gt_i32 s14, 31
	s_cselect_b64 s[36:37], -1, 0
	s_cmp_lt_i32 s14, 32
	s_cselect_b64 s[0:1], -1, 0
	s_cmp_lt_i32 s12, 2
	v_lshl_add_u32 v220, s14, 8, v236
	s_cselect_b64 s[14:15], -1, 0
	s_ashr_i32 s13, s12, 31
	s_and_b64 s[14:15], s[0:1], s[14:15]
	s_mov_b32 s98, s14
	s_lshl_b64 s[0:1], s[12:13], 11
	v_lshl_or_b32 v4, s62, 8, v248
	s_add_u32 s0, s68, s0
	s_addc_u32 s1, s69, s1
	v_ashrrev_i32_e32 v5, 31, v4
	s_mov_b64 s[30:31], -1
	v_lshl_add_u64 v[184:185], s[0:1], 0, v[4:5]
	v_ashrrev_i32_e32 v221, 31, v220
	s_and_b64 vcc, exec, s[14:15]
	v_or_b32_e32 v212, 16, v220
	v_or_b32_e32 v202, 32, v220
	v_or_b32_e32 v188, 48, v220
	v_add_u32_e32 v178, 0x80, v220
	v_add_u32_e32 v168, 0x90, v220
	v_add_u32_e32 v156, 0xa0, v220
	v_add_u32_e32 v148, 0xb0, v220
	s_cbranch_vccnz .LBB0_752
	v_mad_i64_i32 v[152:153], s[0:1], v212, s7, v[184:185]
	v_mad_i64_i32 v[160:161], s[0:1], v202, s7, v[184:185]
	v_mad_i64_i32 v[164:165], s[0:1], v188, s7, v[184:185]
	v_mad_i64_i32 v[170:171], s[0:1], v178, s7, v[184:185]
	v_mad_i64_i32 v[174:175], s[0:1], v168, s7, v[184:185]
	v_mad_i64_i32 v[228:229], s[0:1], v156, s7, v[184:185]
	v_mad_i64_i32 v[230:231], s[0:1], v148, s7, v[184:185]
	s_mov_b64 s[30:31], 0

.LBB0_754:
	global_load_dwordx2 v[238:239], v[180:181], off
	global_load_dwordx2 v[226:227], v[180:181], off offset:128
	global_load_dwordx2 v[224:225], v[152:153], off
	global_load_dwordx2 v[218:219], v[152:153], off offset:128
	global_load_dwordx2 v[214:215], v[160:161], off
	global_load_dwordx2 v[208:209], v[160:161], off offset:128
	global_load_dwordx2 v[204:205], v[164:165], off
	global_load_dwordx2 v[194:195], v[164:165], off offset:128
	global_load_dwordx2 v[190:191], v[170:171], off
	global_load_dwordx2 v[184:185], v[170:171], off offset:128
	global_load_dwordx2 v[180:181], v[174:175], off
	s_nop 0
	global_load_dwordx2 v[174:175], v[174:175], off offset:128
	s_nop 0
	global_load_dwordx2 v[170:171], v[228:229], off
	global_load_dwordx2 v[164:165], v[228:229], off offset:128
	global_load_dwordx2 v[160:161], v[230:231], off
	global_load_dwordx2 v[152:153], v[230:231], off offset:128
	s_xor_b64 s[0:1], s[14:15], -1
	v_cndmask_b32_e64 v3, 0, 1, s[0:1]
	v_cmp_ne_u32_e64 s[12:13], 1, v3
	s_andn2_b64 vcc, exec, s[0:1]
	s_mov_b64 s[14:15], -1
	s_waitcnt vmcnt(15)
	v_cvt_f32_ubyte1_e32 v233, v238
	v_cvt_f32_ubyte0_e32 v232, v238
	v_cvt_f32_ubyte3_e32 v235, v238
	v_cvt_f32_ubyte2_e32 v234, v238
	v_cvt_f32_ubyte1_e32 v229, v239
	v_cvt_f32_ubyte0_e32 v228, v239
	v_cvt_f32_ubyte3_e32 v231, v239
	v_cvt_f32_ubyte2_e32 v230, v239
	s_cbranch_vccnz .LBB0_760
	v_mul_f32_e32 v3, 0x3b808081, v232
	v_mul_f32_e32 v157, 0x3b808081, v233
	v_mul_f32_e32 v169, 0x3b808081, v234
	v_mul_f32_e32 v198, 0x3b808081, v235
	v_mul_f32_e32 v149, v130, v3
	v_mul_f32_e32 v3, 0x3b808081, v228
	v_mul_f32_e32 v179, v131, v157
	v_mul_f32_e32 v157, 0x3b808081, v229
	v_mul_f32_e32 v189, v132, v169
	v_mul_f32_e32 v169, 0x3b808081, v230
	v_mul_f32_e32 v213, v133, v198
	v_mul_f32_e32 v198, 0x3b808081, v231
	v_mul_f32_e32 v3, v126, v3
	v_mul_f32_e32 v157, v127, v157
	v_mul_f32_e32 v169, v128, v169
	v_mul_f32_e32 v203, v129, v198
	s_and_b64 vcc, exec, s[36:37]
	s_cbranch_vccz .LBB0_757
	s_ashr_i32 s65, s64, 31
	s_lshl_b64 s[0:1], s[64:65], 21
	s_add_u32 s0, s77, s0
	s_addc_u32 s1, s78, s1
	v_lshlrev_b64 v[198:199], 12, v[220:221]
	v_lshl_add_u64 v[198:199], s[0:1], 0, v[198:199]
	v_lshl_add_u64 v[198:199], v[4:5], 1, v[198:199]
	v_add_co_u32_e32 v198, vcc, 0xfe000000, v198
	v_cvt_pk_bf16_f32 v238, v149, v179
	v_cvt_pk_bf16_f32 v239, v189, v213
	v_cvt_pk_bf16_f32 v240, v3, v157
	v_cvt_pk_bf16_f32 v241, v169, v203
	s_nop 1
	v_addc_co_u32_e32 v199, vcc, -1, v199, vcc
	global_store_dwordx4 v[198:199], v[238:241], off
	s_mov_b64 s[14:15], 0

.LBB0_762:
	v_cndmask_b32_e64 v3, 0, 1, s[36:37]
	v_or_b32_e32 v158, 0x80, v4
	s_cmp_lg_u32 s98, 0
	s_cbranch_scc1 .Lx_gw_r1
	s_waitcnt vmcnt(15)
	s_branch .Lx_gw_d1

.Lx_gw_d1:
	v_cvt_f32_ubyte1_e32 v233, v226
	v_cvt_f32_ubyte0_e32 v232, v226
	v_cvt_f32_ubyte3_e32 v235, v226
	v_cvt_f32_ubyte2_e32 v234, v226
	v_cvt_f32_ubyte1_e32 v229, v227
	v_cvt_f32_ubyte0_e32 v228, v227
	v_cvt_f32_ubyte3_e32 v231, v227
	v_cvt_f32_ubyte2_e32 v230, v227
	s_mov_b64 s[30:31], -1
	s_and_b64 vcc, exec, s[12:13]
	v_cmp_ne_u32_e64 s[14:15], 1, v3
	s_cbranch_vccnz .LBB0_768
	v_mul_f32_e32 v159, 0x3b808081, v234
	v_mul_f32_e32 v189, v100, v159
	v_mul_f32_e32 v159, 0x3b808081, v230
	v_mul_f32_e32 v3, 0x3b808081, v232
	v_mul_f32_e32 v157, 0x3b808081, v233
	v_mul_f32_e32 v169, v96, v159
	v_mul_f32_e32 v159, 0x3b808081, v235
	v_mul_f32_e32 v149, v98, v3
	v_mul_f32_e32 v3, 0x3b808081, v228
	v_mul_f32_e32 v179, v99, v157
	v_mul_f32_e32 v157, 0x3b808081, v229
	v_mul_f32_e32 v213, v101, v159
	v_mul_f32_e32 v159, 0x3b808081, v231
	v_mul_f32_e32 v3, v94, v3
	v_mul_f32_e32 v157, v95, v157
	v_mul_f32_e32 v203, v97, v159
	s_and_b64 vcc, exec, s[14:15]
	v_lshlrev_b64 v[220:221], 12, v[220:221]
	s_cbranch_vccnz .LBB0_765
	s_ashr_i32 s65, s64, 31
	s_lshl_b64 s[0:1], s[64:65], 21
	s_add_u32 s0, s77, s0
	s_addc_u32 s1, s78, s1
	v_ashrrev_i32_e32 v159, 31, v158
	v_lshl_add_u64 v[198:199], s[0:1], 0, v[220:221]
	v_lshl_add_u64 v[198:199], v[158:159], 1, v[198:199]
	v_add_co_u32_e32 v198, vcc, 0xfe000000, v198
	s_mov_b64 s[30:31], 0
	s_nop 0
	v_addc_co_u32_e32 v199, vcc, -1, v199, vcc
	v_cvt_pk_bf16_f32 v238, v149, v179
	v_cvt_pk_bf16_f32 v239, v189, v213
	v_cvt_pk_bf16_f32 v240, v3, v157
	v_cvt_pk_bf16_f32 v241, v169, v203
	global_store_dwordx4 v[198:199], v[238:241], off

.LBB0_770:
	v_ashrrev_i32_e32 v213, 31, v212
	s_cmp_lg_u32 s98, 0
	s_cbranch_scc1 .Lx_gw_r2
	s_waitcnt vmcnt(15)
	s_branch .Lx_gw_d2
.Lx_gw_r2:
	s_waitcnt vmcnt(13)
.Lx_gw_d2:
	v_cvt_f32_ubyte1_e32 v227, v224
	v_cvt_f32_ubyte0_e32 v226, v224
	v_cvt_f32_ubyte3_e32 v229, v224
	v_cvt_f32_ubyte2_e32 v228, v224
	v_cvt_f32_ubyte1_e32 v221, v225
	v_cvt_f32_ubyte0_e32 v220, v225
	v_cvt_f32_ubyte3_e32 v223, v225
	v_cvt_f32_ubyte2_e32 v222, v225
	s_and_b64 vcc, exec, s[12:13]
	s_mov_b64 s[30:31], -1
	s_cbranch_vccnz .LBB0_776
	v_mul_f32_e32 v3, 0x3b808081, v226
	v_mul_f32_e32 v157, 0x3b808081, v227
	v_mul_f32_e32 v159, 0x3b808081, v228
	v_mul_f32_e32 v189, 0x3b808081, v229
	v_mul_f32_e32 v149, v122, v3
	v_mul_f32_e32 v3, 0x3b808081, v220
	v_mul_f32_e32 v169, v123, v157
	v_mul_f32_e32 v157, 0x3b808081, v221
	v_mul_f32_e32 v179, v124, v159
	v_mul_f32_e32 v159, 0x3b808081, v222
	v_mul_f32_e32 v203, v125, v189
	v_mul_f32_e32 v189, 0x3b808081, v223
	v_mul_f32_e32 v3, v118, v3
	v_mul_f32_e32 v157, v119, v157
	v_mul_f32_e32 v159, v120, v159
	v_mul_f32_e32 v189, v121, v189
	s_and_b64 vcc, exec, s[14:15]
	s_cbranch_vccnz .LBB0_773
	s_ashr_i32 s65, s64, 31
	s_lshl_b64 s[0:1], s[64:65], 21
	s_add_u32 s0, s77, s0
	s_addc_u32 s1, s78, s1
	v_lshlrev_b64 v[198:199], 12, v[212:213]
	v_lshl_add_u64 v[198:199], s[0:1], 0, v[198:199]
	v_lshl_add_u64 v[198:199], v[4:5], 1, v[198:199]
	v_add_co_u32_e32 v198, vcc, 0xfe000000, v198
	s_mov_b64 s[30:31], 0
	s_nop 0
	v_addc_co_u32_e32 v199, vcc, -1, v199, vcc
	v_cvt_pk_bf16_f32 v230, v149, v169
	v_cvt_pk_bf16_f32 v231, v179, v203
	v_cvt_pk_bf16_f32 v232, v3, v157
	v_cvt_pk_bf16_f32 v233, v159, v189
	global_store_dwordx4 v[198:199], v[230:233], off

.LBB0_778:
	s_cmp_lg_u32 s98, 0
	s_cbranch_scc1 .Lx_gw_r3
	s_waitcnt vmcnt(15)
	s_branch .Lx_gw_d3
.Lx_gw_r3:
	s_waitcnt vmcnt(12)

.LBB0_786:
	v_ashrrev_i32_e32 v203, 31, v202
	s_cmp_lg_u32 s98, 0
	s_cbranch_scc1 .Lx_gw_r4
	s_waitcnt vmcnt(15)
	s_branch .Lx_gw_d4
.Lx_gw_r4:
	s_waitcnt vmcnt(11)
.Lx_gw_d4:
	v_cvt_f32_ubyte1_e32 v217, v214
	v_cvt_f32_ubyte0_e32 v216, v214
	v_cvt_f32_ubyte3_e32 v219, v214
	v_cvt_f32_ubyte2_e32 v218, v214
	v_cvt_f32_ubyte1_e32 v211, v215
	v_cvt_f32_ubyte0_e32 v210, v215
	v_cvt_f32_ubyte3_e32 v213, v215
	v_cvt_f32_ubyte2_e32 v212, v215
	s_and_b64 vcc, exec, s[12:13]
	s_mov_b64 s[30:31], -1
	s_cbranch_vccnz .LBB0_792
	v_mul_f32_e32 v3, 0x3b808081, v216
	v_mul_f32_e32 v157, 0x3b808081, v217
	v_mul_f32_e32 v159, 0x3b808081, v218
	v_mul_f32_e32 v189, 0x3b808081, v219
	v_mul_f32_e32 v149, v114, v3
	v_mul_f32_e32 v3, 0x3b808081, v210
	v_mul_f32_e32 v169, v115, v157
	v_mul_f32_e32 v157, 0x3b808081, v211
	v_mul_f32_e32 v179, v116, v159
	v_mul_f32_e32 v159, 0x3b808081, v212
	v_mul_f32_e32 v214, v117, v189
	v_mul_f32_e32 v189, 0x3b808081, v213
	v_mul_f32_e32 v3, v110, v3
	v_mul_f32_e32 v157, v111, v157
	v_mul_f32_e32 v159, v112, v159
	v_mul_f32_e32 v189, v113, v189
	s_and_b64 vcc, exec, s[14:15]
	s_cbranch_vccnz .LBB0_789
	s_ashr_i32 s65, s64, 31
	s_lshl_b64 s[0:1], s[64:65], 21
	s_add_u32 s0, s77, s0
	s_addc_u32 s1, s78, s1
	v_lshlrev_b64 v[198:199], 12, v[202:203]
	v_lshl_add_u64 v[198:199], s[0:1], 0, v[198:199]
	v_lshl_add_u64 v[198:199], v[4:5], 1, v[198:199]
	v_add_co_u32_e32 v198, vcc, 0xfe000000, v198
	s_mov_b64 s[30:31], 0
	s_nop 0
	v_addc_co_u32_e32 v199, vcc, -1, v199, vcc
	v_cvt_pk_bf16_f32 v220, v149, v169
	v_cvt_pk_bf16_f32 v221, v179, v214
	v_cvt_pk_bf16_f32 v222, v3, v157
	v_cvt_pk_bf16_f32 v223, v159, v189
	global_store_dwordx4 v[198:199], v[220:223], off

.Lx_gw_r5:
	s_waitcnt vmcnt(10)

.LBB0_802:
	v_ashrrev_i32_e32 v189, 31, v188
	s_cmp_lg_u32 s98, 0
	s_cbranch_scc1 .Lx_gw_r6
	s_waitcnt vmcnt(15)
	s_branch .Lx_gw_d6
.Lx_gw_r6:
	s_waitcnt vmcnt(9)
.Lx_gw_d6:
	v_cvt_f32_ubyte1_e32 v207, v204
	v_cvt_f32_ubyte0_e32 v206, v204
	v_cvt_f32_ubyte3_e32 v209, v204
	v_cvt_f32_ubyte2_e32 v208, v204
	v_cvt_f32_ubyte1_e32 v201, v205
	v_cvt_f32_ubyte0_e32 v200, v205
	v_cvt_f32_ubyte3_e32 v203, v205
	v_cvt_f32_ubyte2_e32 v202, v205
	s_and_b64 vcc, exec, s[12:13]
	s_mov_b64 s[30:31], -1
	s_cbranch_vccnz .LBB0_808
	v_mul_f32_e32 v3, 0x3b808081, v206
	v_mul_f32_e32 v157, 0x3b808081, v207
	v_mul_f32_e32 v159, 0x3b808081, v208
	v_mul_f32_e32 v198, 0x3b808081, v209
	v_mul_f32_e32 v149, v106, v3
	v_mul_f32_e32 v3, 0x3b808081, v200
	v_mul_f32_e32 v169, v107, v157
	v_mul_f32_e32 v157, 0x3b808081, v201
	v_mul_f32_e32 v179, v108, v159
	v_mul_f32_e32 v159, 0x3b808081, v202
	v_mul_f32_e32 v205, v109, v198
	v_mul_f32_e32 v198, 0x3b808081, v203
	v_mul_f32_e32 v3, v102, v3
	v_mul_f32_e32 v157, v103, v157
	v_mul_f32_e32 v159, v104, v159
	v_mul_f32_e32 v204, v105, v198
	s_and_b64 vcc, exec, s[14:15]
	s_cbranch_vccnz .LBB0_805
	s_ashr_i32 s65, s64, 31
	s_lshl_b64 s[0:1], s[64:65], 21
	s_add_u32 s0, s77, s0
	s_addc_u32 s1, s78, s1
	v_lshlrev_b64 v[198:199], 12, v[188:189]
	v_lshl_add_u64 v[198:199], s[0:1], 0, v[198:199]
	v_lshl_add_u64 v[198:199], v[4:5], 1, v[198:199]
	v_add_co_u32_e32 v198, vcc, 0xfe000000, v198
	s_mov_b64 s[30:31], 0
	s_nop 0
	v_addc_co_u32_e32 v199, vcc, -1, v199, vcc
	v_cvt_pk_bf16_f32 v210, v149, v169
	v_cvt_pk_bf16_f32 v211, v179, v205
	v_cvt_pk_bf16_f32 v212, v3, v157
	v_cvt_pk_bf16_f32 v213, v159, v204
	global_store_dwordx4 v[198:199], v[210:213], off

.Lx_gw_r7:
	s_waitcnt vmcnt(8)

.LBB0_818:
	v_ashrrev_i32_e32 v179, 31, v178
	s_cmp_lg_u32 s98, 0
	s_cbranch_scc1 .Lx_gw_r8
	s_waitcnt vmcnt(15)
	s_branch .Lx_gw_d8

.Lx_gw_d8:
	v_cvt_f32_ubyte1_e32 v193, v190
	v_cvt_f32_ubyte0_e32 v192, v190
	v_cvt_f32_ubyte3_e32 v195, v190
	v_cvt_f32_ubyte2_e32 v194, v190
	v_cvt_f32_ubyte1_e32 v187, v191
	v_cvt_f32_ubyte0_e32 v186, v191
	v_cvt_f32_ubyte3_e32 v189, v191
	v_cvt_f32_ubyte2_e32 v188, v191
	s_and_b64 vcc, exec, s[12:13]
	s_mov_b64 s[30:31], -1
	s_cbranch_vccnz .LBB0_824
	v_mul_f32_e32 v3, 0x3b808081, v192
	v_mul_f32_e32 v157, 0x3b808081, v193
	v_mul_f32_e32 v159, 0x3b808081, v194
	v_mul_f32_e32 v191, 0x3b808081, v195
	v_mul_f32_e32 v149, v66, v3
	v_mul_f32_e32 v3, 0x3b808081, v186
	v_mul_f32_e32 v169, v67, v157
	v_mul_f32_e32 v157, 0x3b808081, v187
	v_mul_f32_e32 v190, v68, v159
	v_mul_f32_e32 v159, 0x3b808081, v188
	v_mul_f32_e32 v200, v69, v191
	v_mul_f32_e32 v191, 0x3b808081, v189
	v_mul_f32_e32 v3, v62, v3
	v_mul_f32_e32 v157, v63, v157
	v_mul_f32_e32 v159, v64, v159
	v_mul_f32_e32 v191, v65, v191
	s_and_b64 vcc, exec, s[14:15]
	s_cbranch_vccnz .LBB0_821
	s_ashr_i32 s65, s64, 31
	s_lshl_b64 s[0:1], s[64:65], 21
	s_add_u32 s0, s77, s0
	s_addc_u32 s1, s78, s1
	v_lshlrev_b64 v[198:199], 12, v[178:179]
	v_lshl_add_u64 v[198:199], s[0:1], 0, v[198:199]
	v_lshl_add_u64 v[198:199], v[4:5], 1, v[198:199]
	v_add_co_u32_e32 v198, vcc, 0xfe000000, v198
	s_mov_b64 s[30:31], 0
	s_nop 0
	v_addc_co_u32_e32 v199, vcc, -1, v199, vcc
	v_cvt_pk_bf16_f32 v202, v149, v169
	v_cvt_pk_bf16_f32 v203, v190, v200
	v_cvt_pk_bf16_f32 v204, v3, v157
	v_cvt_pk_bf16_f32 v205, v159, v191
	global_store_dwordx4 v[198:199], v[202:205], off

.Lx_gw_r9:
	s_waitcnt vmcnt(6)

.LBB0_834:
	v_ashrrev_i32_e32 v169, 31, v168
	s_cmp_lg_u32 s98, 0
	s_cbranch_scc1 .Lx_gw_r10
	s_waitcnt vmcnt(15)
	s_branch .Lx_gw_d10

.Lx_gw_d10:
	v_cvt_f32_ubyte1_e32 v183, v180
	v_cvt_f32_ubyte0_e32 v182, v180
	v_cvt_f32_ubyte3_e32 v185, v180
	v_cvt_f32_ubyte2_e32 v184, v180
	v_cvt_f32_ubyte1_e32 v177, v181
	v_cvt_f32_ubyte0_e32 v176, v181
	v_cvt_f32_ubyte3_e32 v179, v181
	v_cvt_f32_ubyte2_e32 v178, v181
	s_and_b64 vcc, exec, s[12:13]
	s_mov_b64 s[30:31], -1
	s_cbranch_vccnz .LBB0_840
	v_mul_f32_e32 v3, 0x3b808081, v182
	v_mul_f32_e32 v157, 0x3b808081, v183
	v_mul_f32_e32 v159, 0x3b808081, v184
	v_mul_f32_e32 v186, 0x3b808081, v185
	v_mul_f32_e32 v149, v58, v3
	v_mul_f32_e32 v3, 0x3b808081, v176
	v_mul_f32_e32 v180, v59, v157
	v_mul_f32_e32 v157, 0x3b808081, v177
	v_mul_f32_e32 v181, v60, v159
	v_mul_f32_e32 v159, 0x3b808081, v178
	v_mul_f32_e32 v187, v61, v186
	v_mul_f32_e32 v186, 0x3b808081, v179
	v_mul_f32_e32 v3, v54, v3
	v_mul_f32_e32 v157, v55, v157
	v_mul_f32_e32 v159, v56, v159
	v_mul_f32_e32 v186, v57, v186
	s_and_b64 vcc, exec, s[14:15]
	s_cbranch_vccnz .LBB0_837
	s_ashr_i32 s65, s64, 31
	s_lshl_b64 s[0:1], s[64:65], 21
	s_add_u32 s0, s77, s0
	s_addc_u32 s1, s78, s1
	v_lshlrev_b64 v[188:189], 12, v[168:169]
	v_lshl_add_u64 v[188:189], s[0:1], 0, v[188:189]
	v_lshl_add_u64 v[192:193], v[4:5], 1, v[188:189]
	v_add_co_u32_e32 v192, vcc, 0xfe000000, v192
	s_mov_b64 s[30:31], 0
	s_nop 0
	v_addc_co_u32_e32 v193, vcc, -1, v193, vcc
	v_cvt_pk_bf16_f32 v188, v149, v180
	v_cvt_pk_bf16_f32 v189, v181, v187
	v_cvt_pk_bf16_f32 v190, v3, v157
	v_cvt_pk_bf16_f32 v191, v159, v186
	global_store_dwordx4 v[192:193], v[188:191], off

.Lx_gw_r11:
	s_waitcnt vmcnt(4)

.LBB0_850:
	v_ashrrev_i32_e32 v157, 31, v156
	s_cmp_lg_u32 s98, 0
	s_cbranch_scc1 .Lx_gw_r12
	s_waitcnt vmcnt(15)
	s_branch .Lx_gw_d12
.Lx_gw_r12:
	s_waitcnt vmcnt(3)
.Lx_gw_d12:
	v_cvt_f32_ubyte1_e32 v173, v170
	v_cvt_f32_ubyte0_e32 v172, v170
	v_cvt_f32_ubyte3_e32 v175, v170
	v_cvt_f32_ubyte2_e32 v174, v170
	v_cvt_f32_ubyte1_e32 v167, v171
	v_cvt_f32_ubyte0_e32 v166, v171
	v_cvt_f32_ubyte3_e32 v169, v171
	v_cvt_f32_ubyte2_e32 v168, v171
	s_and_b64 vcc, exec, s[12:13]
	s_mov_b64 s[30:31], -1
	s_cbranch_vccnz .LBB0_856
	v_mul_f32_e32 v3, 0x3b808081, v172
	v_mul_f32_e32 v159, 0x3b808081, v173
	v_mul_f32_e32 v170, 0x3b808081, v174
	v_mul_f32_e32 v177, 0x3b808081, v175
	v_mul_f32_e32 v149, v50, v3
	v_mul_f32_e32 v3, 0x3b808081, v166
	v_mul_f32_e32 v171, v51, v159
	v_mul_f32_e32 v159, 0x3b808081, v167
	v_mul_f32_e32 v176, v52, v170
	v_mul_f32_e32 v170, 0x3b808081, v168
	v_mul_f32_e32 v178, v53, v177
	v_mul_f32_e32 v177, 0x3b808081, v169
	v_mul_f32_e32 v3, v46, v3
	v_mul_f32_e32 v159, v47, v159
	v_mul_f32_e32 v170, v48, v170
	v_mul_f32_e32 v177, v49, v177
	s_and_b64 vcc, exec, s[14:15]
	s_cbranch_vccnz .LBB0_853
	s_ashr_i32 s65, s64, 31
	s_lshl_b64 s[0:1], s[64:65], 21
	s_add_u32 s0, s77, s0
	s_addc_u32 s1, s78, s1
	v_lshlrev_b64 v[180:181], 12, v[156:157]
	v_lshl_add_u64 v[180:181], s[0:1], 0, v[180:181]
	v_lshl_add_u64 v[184:185], v[4:5], 1, v[180:181]
	v_add_co_u32_e32 v184, vcc, 0xfe000000, v184
	s_mov_b64 s[30:31], 0
	s_nop 0
	v_addc_co_u32_e32 v185, vcc, -1, v185, vcc
	v_cvt_pk_bf16_f32 v180, v149, v171
	v_cvt_pk_bf16_f32 v181, v176, v178
	v_cvt_pk_bf16_f32 v182, v3, v159
	v_cvt_pk_bf16_f32 v183, v170, v177
	global_store_dwordx4 v[184:185], v[180:183], off

.Lx_gw_r13:
	s_waitcnt vmcnt(2)

.LBB0_866:
	v_ashrrev_i32_e32 v149, 31, v148
	s_cmp_lg_u32 s98, 0
	s_cbranch_scc1 .Lx_gw_r14
	s_waitcnt vmcnt(15)
	s_branch .Lx_gw_d14

.Lx_gw_d14:
	v_cvt_f32_ubyte1_e32 v163, v160
	v_cvt_f32_ubyte0_e32 v162, v160
	v_cvt_f32_ubyte3_e32 v165, v160
	v_cvt_f32_ubyte2_e32 v164, v160
	v_cvt_f32_ubyte1_e32 v155, v161
	v_cvt_f32_ubyte0_e32 v154, v161
	v_cvt_f32_ubyte3_e32 v157, v161
	v_cvt_f32_ubyte2_e32 v156, v161
	s_and_b64 vcc, exec, s[12:13]
	s_mov_b64 s[30:31], -1
	s_cbranch_vccnz .LBB0_872
	v_mul_f32_e32 v3, 0x3b808081, v162
	v_mul_f32_e32 v160, 0x3b808081, v163
	v_mul_f32_e32 v161, 0x3b808081, v164
	v_mul_f32_e32 v168, 0x3b808081, v165
	v_mul_f32_e32 v159, v42, v3
	v_mul_f32_e32 v3, 0x3b808081, v154
	v_mul_f32_e32 v166, v43, v160
	v_mul_f32_e32 v160, 0x3b808081, v155
	v_mul_f32_e32 v167, v44, v161
	v_mul_f32_e32 v161, 0x3b808081, v156
	v_mul_f32_e32 v169, v45, v168
	v_mul_f32_e32 v168, 0x3b808081, v157
	v_mul_f32_e32 v3, v38, v3
	v_mul_f32_e32 v160, v39, v160
	v_mul_f32_e32 v161, v40, v161
	v_mul_f32_e32 v168, v41, v168
	s_and_b64 vcc, exec, s[14:15]
	s_cbranch_vccnz .LBB0_869
	s_ashr_i32 s65, s64, 31
	s_lshl_b64 s[0:1], s[64:65], 21
	s_add_u32 s0, s77, s0
	s_addc_u32 s1, s78, s1
	v_lshlrev_b64 v[170:171], 12, v[148:149]
	v_lshl_add_u64 v[170:171], s[0:1], 0, v[170:171]
	v_lshl_add_u64 v[174:175], v[4:5], 1, v[170:171]
	v_add_co_u32_e32 v174, vcc, 0xfe000000, v174
	s_mov_b64 s[30:31], 0
	s_nop 0
	v_addc_co_u32_e32 v175, vcc, -1, v175, vcc
	v_cvt_pk_bf16_f32 v170, v159, v166
	v_cvt_pk_bf16_f32 v171, v167, v169
	v_cvt_pk_bf16_f32 v172, v3, v160
	v_cvt_pk_bf16_f32 v173, v161, v168
	global_store_dwordx4 v[174:175], v[170:173], off

.Lx_gw_r15:
	s_waitcnt vmcnt(0)
.Lx_gw_d15:
	v_cvt_f32_ubyte1_e32 v157, v152
	v_cvt_f32_ubyte0_e32 v156, v152
	v_cvt_f32_ubyte3_e32 v161, v152
	v_cvt_f32_ubyte2_e32 v160, v152
	v_cvt_f32_ubyte1_e32 v151, v153
	v_cvt_f32_ubyte0_e32 v150, v153
	v_cvt_f32_ubyte3_e32 v155, v153
	v_cvt_f32_ubyte2_e32 v154, v153
	s_and_b64 vcc, exec, s[12:13]
	s_mov_b64 s[12:13], -1
	s_cbranch_vccnz .LBB0_880
	v_mul_f32_e32 v159, 0x3b808081, v160
	v_mul_f32_e32 v164, v12, v159
	v_mul_f32_e32 v159, 0x3b808081, v154
	v_mul_f32_e32 v3, 0x3b808081, v156
	v_mul_f32_e32 v153, 0x3b808081, v157
	v_mul_f32_e32 v162, v8, v159
	v_mul_f32_e32 v159, 0x3b808081, v161
	v_mul_f32_e32 v152, v10, v3
	v_mul_f32_e32 v3, 0x3b808081, v150
	v_mul_f32_e32 v163, v11, v153
	v_mul_f32_e32 v153, 0x3b808081, v151
	v_mul_f32_e32 v166, v13, v159
	v_mul_f32_e32 v159, 0x3b808081, v155
	v_mul_f32_e32 v3, v6, v3
	v_mul_f32_e32 v153, v7, v153
	v_mul_f32_e32 v165, v9, v159
	s_and_b64 vcc, exec, s[14:15]
	v_lshlrev_b64 v[148:149], 12, v[148:149]
	s_cbranch_vccnz .LBB0_877
	s_ashr_i32 s65, s64, 31
	s_lshl_b64 s[0:1], s[64:65], 21
	s_add_u32 s0, s77, s0
	s_addc_u32 s1, s78, s1
	v_ashrrev_i32_e32 v159, 31, v158
	v_lshl_add_u64 v[168:169], s[0:1], 0, v[148:149]
	v_lshl_add_u64 v[158:159], v[158:159], 1, v[168:169]
	v_add_co_u32_e32 v158, vcc, 0xfe000000, v158
	s_mov_b64 s[12:13], 0
	s_nop 0
	v_addc_co_u32_e32 v159, vcc, -1, v159, vcc
	v_cvt_pk_bf16_f32 v168, v152, v163
	v_cvt_pk_bf16_f32 v169, v164, v166
	v_cvt_pk_bf16_f32 v170, v3, v153
	v_cvt_pk_bf16_f32 v171, v162, v165
	global_store_dwordx4 v[158:159], v[168:171], off
